# attention: the 8 masked bias lookups of the edge key tiles issued together instead of 8 serialized LDS round trips
# baseline (speedup 1.0000x reference)
.LBB0_334:
	v_mul_f32_e32 v0, 0x4b800000, v84
	v_cndmask_b32_e64 v0, v84, v0, s[82:83]
	v_rsq_f32_e32 v0, v0
	s_waitcnt lgkmcnt(0)
	s_barrier
	v_mul_f32_e32 v84, 0x45800000, v0
	v_cndmask_b32_e64 v0, v0, v84, s[82:83]
	v_mul_f32_e32 v0, 0x3e000000, v0
	v_mul_f32_e32 v0, 0x3fb8aa3b, v0
	v_pk_mul_f32 v[76:77], v[0:1], v[76:77] op_sel_hi:[0,1]
	v_pk_mul_f32 v[74:75], v[0:1], v[74:75] op_sel_hi:[0,1]
	v_pk_mul_f32 v[76:77], v[14:15], v[76:77]
	v_pk_mul_f32 v[74:75], v[24:25], v[74:75]
	v_cvt_pk_bf16_f32 v91, v76, v77
	v_cvt_pk_bf16_f32 v140, v74, v75
	ds_read_b128 v[74:77], v239
	v_pk_mul_f32 v[80:81], v[0:1], v[80:81] op_sel_hi:[0,1]
	v_pk_mul_f32 v[78:79], v[0:1], v[78:79] op_sel_hi:[0,1]
	v_pk_mul_f32 v[80:81], v[18:19], v[80:81]
	v_pk_mul_f32 v[78:79], v[12:13], v[78:79]
	v_cvt_pk_bf16_f32 v89, v80, v81
	v_cvt_pk_bf16_f32 v90, v78, v79
	ds_read_b128 v[78:81], v239 offset:64
	v_pk_mul_f32 v[82:83], v[0:1], v[82:83] op_sel_hi:[0,1]
	v_pk_mul_f32 v[82:83], v[16:17], v[82:83]
	v_pk_mul_f32 v[72:73], v[0:1], v[72:73] op_sel_hi:[0,1]
	v_pk_mul_f32 v[70:71], v[0:1], v[70:71] op_sel_hi:[0,1]
	v_cvt_pk_bf16_f32 v88, v82, v83
	v_pk_mul_f32 v[72:73], v[26:27], v[72:73]
	v_pk_mul_f32 v[70:71], v[20:21], v[70:71]
	v_cvt_pk_bf16_f32 v141, v72, v73
	v_cvt_pk_bf16_f32 v142, v70, v71
	v_pk_mul_f32 v[82:83], v[0:1], v[68:69] op_sel_hi:[0,1]
	s_waitcnt lgkmcnt(1)
	v_mfma_f32_16x16x32_bf16 v[68:71], v[74:77], v[88:91], 0
	ds_read_b128 v[72:75], v240
	v_pk_mul_f32 v[76:77], v[22:23], v[82:83]
	ds_read_b128 v[144:147], v247
	v_cvt_pk_bf16_f32 v143, v76, v77
	s_and_b32 s0, s58, s56
	s_and_b32 s0, s0, 0x7f
	s_waitcnt lgkmcnt(2)
	v_mfma_f32_16x16x32_bf16 v[108:111], v[78:81], v[140:143], v[68:71]
	ds_read_b128 v[76:79], v241
	s_cmp_lg_u32 s0, 0
	s_nop 0
	ds_read_b128 v[68:71], v240 offset:64
	s_waitcnt lgkmcnt(3)
	v_mfma_f32_16x16x32_bf16 v[72:75], v[72:75], v[88:91], 0
	s_waitcnt lgkmcnt(0)
	v_mfma_f32_16x16x32_bf16 v[104:107], v[68:71], v[140:143], v[72:75]
	ds_read_b128 v[68:71], v241 offset:64
	v_mfma_f32_16x16x32_bf16 v[72:75], v[76:79], v[88:91], 0
	ds_read_b128 v[76:79], v242
	s_waitcnt lgkmcnt(1)
	v_mfma_f32_16x16x32_bf16 v[100:103], v[68:71], v[140:143], v[72:75]
	ds_read_b128 v[68:71], v242 offset:64
	s_waitcnt lgkmcnt(1)
	v_mfma_f32_16x16x32_bf16 v[72:75], v[76:79], v[88:91], 0
	ds_read_b128 v[76:79], v243
	s_waitcnt lgkmcnt(1)
	v_mfma_f32_16x16x32_bf16 v[96:99], v[68:71], v[140:143], v[72:75]
	ds_read_b128 v[68:71], v243 offset:64
	s_waitcnt lgkmcnt(1)
	v_mfma_f32_16x16x32_bf16 v[72:75], v[76:79], v[88:91], 0
	ds_read_b128 v[76:79], v244
	s_waitcnt lgkmcnt(1)
	v_mfma_f32_16x16x32_bf16 v[92:95], v[68:71], v[140:143], v[72:75]
	ds_read_b128 v[68:71], v244 offset:64
	s_waitcnt lgkmcnt(1)
	v_mfma_f32_16x16x32_bf16 v[72:75], v[76:79], v[88:91], 0
	ds_read_b128 v[76:79], v245
	s_waitcnt lgkmcnt(1)
	v_mfma_f32_16x16x32_bf16 v[84:87], v[68:71], v[140:143], v[72:75]
	ds_read_b128 v[68:71], v245 offset:64
	s_waitcnt lgkmcnt(1)
	v_mfma_f32_16x16x32_bf16 v[72:75], v[76:79], v[88:91], 0
	ds_read_b128 v[76:79], v246
	s_waitcnt lgkmcnt(1)
	v_mfma_f32_16x16x32_bf16 v[80:83], v[68:71], v[140:143], v[72:75]
	ds_read_b128 v[68:71], v246 offset:64
	s_waitcnt lgkmcnt(1)
	v_mfma_f32_16x16x32_bf16 v[72:75], v[76:79], v[88:91], 0
	s_waitcnt lgkmcnt(0)
	v_mfma_f32_16x16x32_bf16 v[76:79], v[68:71], v[140:143], v[72:75]
	ds_read_b128 v[68:71], v247 offset:64
	v_mfma_f32_16x16x32_bf16 v[72:75], v[144:147], v[88:91], 0
	s_waitcnt lgkmcnt(0)
	v_mfma_f32_16x16x32_bf16 v[72:75], v[68:71], v[140:143], v[72:75]
	s_cbranch_scc0 .LBB0_352
	v_mov_b32_e32 v68, 0xff800000
	v_mov_b32_e32 v69, 0xff800000
	v_mov_b32_e32 v70, 0xff800000
	v_mov_b32_e32 v71, 0xff800000
	v_mov_b32_e32 v88, 0xff800000
	v_mov_b32_e32 v89, 0xff800000
	v_mov_b32_e32 v90, 0xff800000
	v_mov_b32_e32 v91, 0xff800000
	s_mov_b64 s[24:25], exec
	s_and_b64 exec, s[24:25], s[8:9]
	ds_read_b32 v68, v183
	s_and_b64 exec, s[24:25], s[10:11]
	ds_read_b32 v69, v184
	s_and_b64 exec, s[24:25], s[12:13]
	ds_read_b32 v70, v185
	s_and_b64 exec, s[24:25], s[14:15]
	ds_read_b32 v71, v186
	s_and_b64 exec, s[24:25], s[16:17]
	ds_read_b32 v88, v187
	s_and_b64 exec, s[24:25], s[18:19]
	ds_read_b32 v89, v188
	s_and_b64 exec, s[24:25], s[20:21]
	ds_read_b32 v90, v189
	s_and_b64 exec, s[24:25], s[22:23]
	ds_read_b32 v91, v190
	s_mov_b64 exec, s[24:25]
	ds_read2_b32 v[142:143], v187 offset0:111 offset1:112
	ds_read2_b32 v[140:141], v187 offset0:109 offset1:110
	ds_read2_b32 v[144:145], v187 offset0:95 offset1:96
	ds_read2_b32 v[146:147], v187 offset0:93 offset1:94
	ds_read2_b32 v[148:149], v187 offset0:79 offset1:80
	ds_read2_b32 v[150:151], v187 offset0:77 offset1:78
	ds_read2_b32 v[152:153], v187 offset0:63 offset1:64
	ds_read2_b32 v[154:155], v187 offset0:61 offset1:62
	ds_read2_b32 v[156:157], v187 offset0:47 offset1:48
	ds_read2_b32 v[158:159], v187 offset0:45 offset1:46
	ds_read2_b32 v[160:161], v187 offset0:31 offset1:32
	ds_read2_b32 v[166:167], v187 offset0:29 offset1:30
	ds_read2_b32 v[168:169], v187 offset0:15 offset1:16
	ds_read2_b32 v[170:171], v187 offset0:13 offset1:14
	s_waitcnt lgkmcnt(14)
	s_and_b64 exec, s[24:25], s[8:9]
	v_add_f32_e32 v68, v108, v68
	s_and_b64 exec, s[24:25], s[10:11]
	v_add_f32_e32 v69, v109, v69
	s_and_b64 exec, s[24:25], s[12:13]
	v_add_f32_e32 v70, v110, v70
	s_and_b64 exec, s[24:25], s[14:15]
	v_add_f32_e32 v71, v111, v71
	s_and_b64 exec, s[24:25], s[16:17]
	v_add_f32_e32 v88, v72, v88
	s_and_b64 exec, s[24:25], s[18:19]
	v_add_f32_e32 v89, v73, v89
	s_and_b64 exec, s[24:25], s[20:21]
	v_add_f32_e32 v90, v74, v90
	s_and_b64 exec, s[24:25], s[22:23]
	v_add_f32_e32 v91, v75, v91
	s_mov_b64 exec, s[24:25]
	s_mov_b32 s24, 0xff800000
	v_max3_f32 v0, v68, s24, v69
	v_max3_f32 v0, v0, v70, v71
	s_waitcnt lgkmcnt(13)
	v_pk_add_f32 v[142:143], v[104:105], v[142:143] op_sel:[0,1] op_sel_hi:[1,0]
	s_waitcnt lgkmcnt(12)
	v_pk_add_f32 v[140:141], v[106:107], v[140:141] op_sel:[0,1] op_sel_hi:[1,0]
	v_max3_f32 v0, v0, v142, v143
	v_max3_f32 v0, v0, v140, v141
	s_waitcnt lgkmcnt(11)
	v_pk_add_f32 v[144:145], v[100:101], v[144:145] op_sel:[0,1] op_sel_hi:[1,0]
	s_waitcnt lgkmcnt(10)
	v_pk_add_f32 v[146:147], v[102:103], v[146:147] op_sel:[0,1] op_sel_hi:[1,0]
	v_max3_f32 v0, v0, v144, v145
	v_max3_f32 v0, v0, v146, v147
	s_waitcnt lgkmcnt(9)
	v_pk_add_f32 v[148:149], v[96:97], v[148:149] op_sel:[0,1] op_sel_hi:[1,0]
	s_waitcnt lgkmcnt(8)
	v_pk_add_f32 v[150:151], v[98:99], v[150:151] op_sel:[0,1] op_sel_hi:[1,0]
	v_max3_f32 v0, v0, v148, v149
	v_max3_f32 v0, v0, v150, v151
	s_waitcnt lgkmcnt(7)
	v_pk_add_f32 v[152:153], v[92:93], v[152:153] op_sel:[0,1] op_sel_hi:[1,0]
	s_waitcnt lgkmcnt(6)
	v_pk_add_f32 v[154:155], v[94:95], v[154:155] op_sel:[0,1] op_sel_hi:[1,0]
	v_max3_f32 v0, v0, v152, v153
	v_max3_f32 v0, v0, v154, v155
	s_waitcnt lgkmcnt(5)
	v_pk_add_f32 v[156:157], v[84:85], v[156:157] op_sel:[0,1] op_sel_hi:[1,0]
	s_waitcnt lgkmcnt(4)
	v_pk_add_f32 v[158:159], v[86:87], v[158:159] op_sel:[0,1] op_sel_hi:[1,0]
	v_max3_f32 v0, v0, v156, v157
	v_max3_f32 v0, v0, v158, v159
	s_waitcnt lgkmcnt(3)
	v_pk_add_f32 v[160:161], v[80:81], v[160:161] op_sel:[0,1] op_sel_hi:[1,0]
	s_waitcnt lgkmcnt(2)
	v_pk_add_f32 v[166:167], v[82:83], v[166:167] op_sel:[0,1] op_sel_hi:[1,0]
	v_max3_f32 v0, v0, v160, v161
	v_max3_f32 v0, v0, v166, v167
	s_waitcnt lgkmcnt(1)
	v_pk_add_f32 v[168:169], v[76:77], v[168:169] op_sel:[0,1] op_sel_hi:[1,0]
	s_waitcnt lgkmcnt(0)
	v_pk_add_f32 v[170:171], v[78:79], v[170:171] op_sel:[0,1] op_sel_hi:[1,0]
	v_max3_f32 v0, v0, v168, v169
	v_max3_f32 v0, v0, v170, v171
	v_max3_f32 v0, v0, v88, v89
	v_max3_f32 v0, v0, v90, v91
	s_branch .LBB0_426
